# merge k-loop: staging block (LDS writes, address arithmetic, next loads) interleaved behind the MFMAs, on top of A-fragment double buffering
# baseline (speedup 1.0000x reference)
; #define RTID opaque_tid()
; template <int MI, int NJ> ...
;     ...
;   for (int kt = 0; kt < nk; ++kt) {
;     const int buf = kt & 1;
;     {
;       G8STORE(buf ^ 1);
;       const u16* ga_ = (kt + 2 < nk) ? Ag + (kt + 2) * 64 : Ag + nAoff;
;       const u16* gb_ = (kt + 2 < nk) ? Bg + (kt + 2) * 64 : Bg + nBoff;
;       G8LOADP(ga_, gb_);
;     }
;     __builtin_amdgcn_sched_barrier(0);
;     __builtin_amdgcn_s_setprio(1);
;     const u16* a = ra_ + buf * AROWS * 64;
;     const u16* b = rb_ + buf * BROWS * 64;
; #pragma unroll
;     for (int ks = 0; ks < 2; ++ks) {
;       const u16* a_ = ks ? a + dsw : a;
;       const u16* b_ = ks ? b + dsw : b;
;       bf16x8 bfr[NJ];
; #pragma unroll
;       for (int j = 0; j < NJ; ++j) bfr[j] = *(const bf16x8*)(b_ + j * 16 * 64);
; #pragma unroll
;       for (int ih = 0; ih < MI / 4; ++ih) {
;         bf16x8 af[4];
; #pragma unroll
;         for (int i = 0; i < 4; ++i) af[i] = *(const bf16x8*)(a_ + (ih * 4 + i) * 16 * 64);
; #pragma unroll
;         for (int i = 0; i < 4; ++i)
; #pragma unroll
;           for (int j = 0; j < NJ; ++j) acc[ih * 4 + i][j] = mfma16(af[i], bfr[j], acc[ih * 4 + i][j]);
;       }
;     }
;     __builtin_amdgcn_s_setprio(0);
;     __builtin_amdgcn_sched_barrier(0);
;     __syncthreads();
;   }
; __device__ __forceinline__ void phase_merge(const Params& p, u16* smem, volatile LAS unsigned* vb_) {
;     ...
;       const int tid2 = RTID;
; #pragma unroll
;       for (int k = 0; k < 8; ++k) {
;         const int c = tid2 + 512 * k;
;         const int row = c >> 5, ch = c & 31;
;         *(uint4*)(smem + row * 264 + ch * 8) = *(const uint4*)(MG + (size_t)(mt * 128 + row) * 3072 + n * 1024 + nt * 256 + ch * 8);
;       }
;       __syncthreads();
.LBB0_26:
	s_and_b32 s13, s12, 1
	s_xor_b32 s40, s13, 1
	s_cmp_lt_u32 s12, 6
	s_cselect_b64 vcc, -1, 0
	s_setprio 1
	v_lshl_add_u32 v0, s13, 14, v184
	v_lshl_or_b32 v187, s13, 15, v185
	ds_read_b128 v[192:195], v187 offset:32768
	ds_read_b128 v[196:199], v187 offset:34816
	ds_read_b128 v[204:207], v187 offset:36864
	ds_read_b128 v[208:211], v187 offset:38912
	ds_read_b128 v[188:191], v0
	ds_read_b128 v[246:249], v0 offset:2048
	v_add_u32_e32 v187, v187, v186
	s_waitcnt lgkmcnt(1)
	v_mfma_f32_16x16x32_bf16 v[86:89], v[188:191], v[192:195], v[86:89]
	s_waitcnt lgkmcnt(4)
	v_mfma_f32_16x16x32_bf16 v[82:85], v[188:191], v[196:199], v[82:85]
	s_waitcnt lgkmcnt(3)
	v_mfma_f32_16x16x32_bf16 v[78:81], v[188:191], v[204:207], v[78:81]
	s_waitcnt lgkmcnt(2)
	v_mfma_f32_16x16x32_bf16 v[74:77], v[188:191], v[208:211], v[74:77]
	ds_read_b128 v[188:191], v0 offset:4096
	s_waitcnt lgkmcnt(1)
	v_mfma_f32_16x16x32_bf16 v[70:73], v[246:249], v[192:195], v[70:73]
	v_lshl_add_u32 v200, s40, 14, v183
	s_waitcnt vmcnt(5)
	v_mfma_f32_16x16x32_bf16 v[66:69], v[246:249], v[196:199], v[66:69]
	ds_write_b128 v200, v[2:5]
	s_waitcnt vmcnt(3)
	v_mfma_f32_16x16x32_bf16 v[62:65], v[246:249], v[204:207], v[62:65]
	ds_write_b128 v200, v[10:13] offset:8192
	v_lshl_add_u32 v200, s40, 15, v183
	v_mfma_f32_16x16x32_bf16 v[58:61], v[246:249], v[208:211], v[58:61]
	s_waitcnt vmcnt(3)
	ds_write_b128 v200, v[6:9] offset:32768
	ds_read_b128 v[246:249], v0 offset:6144
	v_add_u32_e32 v0, v0, v186
	s_waitcnt lgkmcnt(4)
	v_mfma_f32_16x16x32_bf16 v[54:57], v[188:191], v[192:195], v[54:57]
	s_waitcnt vmcnt(2)
	ds_write_b128 v200, v[14:17] offset:40960
	v_mfma_f32_16x16x32_bf16 v[50:53], v[188:191], v[196:199], v[50:53]
	s_waitcnt vmcnt(1)
	ds_write_b128 v200, v[18:21] offset:49152
	v_mfma_f32_16x16x32_bf16 v[46:49], v[188:191], v[204:207], v[46:49]
	s_waitcnt vmcnt(0)
	ds_write_b128 v200, v[22:25] offset:57344
	v_mfma_f32_16x16x32_bf16 v[42:45], v[188:191], v[208:211], v[42:45]
	v_cndmask_b32_e32 v6, v172, v178, vcc
	v_cndmask_b32_e32 v7, v173, v179, vcc
	ds_read_b128 v[188:191], v0
	s_waitcnt lgkmcnt(4)
	v_mfma_f32_16x16x32_bf16 v[38:41], v[246:249], v[192:195], v[38:41]
	v_cndmask_b32_e32 v11, v177, v181, vcc
	v_cndmask_b32_e32 v10, v176, v180, vcc
	ds_read_b128 v[192:195], v187 offset:32768
	v_mfma_f32_16x16x32_bf16 v[34:37], v[246:249], v[196:199], v[34:37]
	v_add_co_u32_e32 v12, vcc, s77, v6
	s_mov_b32 s40, 0x90000
	ds_read_b128 v[196:199], v187 offset:34816
	v_mfma_f32_16x16x32_bf16 v[30:33], v[246:249], v[204:207], v[30:33]
	s_nop 0
	v_addc_co_u32_e32 v13, vcc, 0, v7, vcc
	ds_read_b128 v[204:207], v187 offset:36864
	v_mfma_f32_16x16x32_bf16 v[26:29], v[246:249], v[208:211], v[26:29]
	v_add_co_u32_e32 v14, vcc, s77, v10
	global_load_dwordx4 v[2:5], v[6:7], off
	ds_read_b128 v[208:211], v187 offset:38912
	ds_read_b128 v[246:249], v0 offset:2048
	s_waitcnt lgkmcnt(4)
	v_mfma_f32_16x16x32_bf16 v[86:89], v[188:191], v[192:195], v[86:89]
	s_nop 0
	v_addc_co_u32_e32 v15, vcc, 0, v11, vcc
	s_waitcnt lgkmcnt(3)
	v_mfma_f32_16x16x32_bf16 v[82:85], v[188:191], v[196:199], v[82:85]
	v_add_co_u32_e32 v18, vcc, s54, v10
	global_load_dwordx4 v[6:9], v[10:11], off
	s_waitcnt lgkmcnt(2)
	v_mfma_f32_16x16x32_bf16 v[78:81], v[188:191], v[204:207], v[78:81]
	s_nop 0
	v_addc_co_u32_e32 v19, vcc, 0, v11, vcc
	s_waitcnt lgkmcnt(1)
	v_mfma_f32_16x16x32_bf16 v[74:77], v[188:191], v[208:211], v[74:77]
	v_add_co_u32_e32 v22, vcc, s40, v10
	s_nop 1
	ds_read_b128 v[188:191], v0 offset:4096
	s_waitcnt lgkmcnt(1)
	v_mfma_f32_16x16x32_bf16 v[70:73], v[246:249], v[192:195], v[70:73]
	v_addc_co_u32_e32 v23, vcc, 0, v11, vcc
	global_load_dwordx4 v[10:13], v[12:13], off
	v_mfma_f32_16x16x32_bf16 v[66:69], v[246:249], v[196:199], v[66:69]
	s_nop 0
	global_load_dwordx4 v[14:17], v[14:15], off
	v_mfma_f32_16x16x32_bf16 v[62:65], v[246:249], v[204:207], v[62:65]
	s_nop 0
	global_load_dwordx4 v[18:21], v[18:19], off
	v_mfma_f32_16x16x32_bf16 v[58:61], v[246:249], v[208:211], v[58:61]
	s_nop 0
	global_load_dwordx4 v[22:25], v[22:23], off
	ds_read_b128 v[246:249], v0 offset:6144
	s_waitcnt lgkmcnt(1)
	v_mfma_f32_16x16x32_bf16 v[54:57], v[188:191], v[192:195], v[54:57]
	v_mfma_f32_16x16x32_bf16 v[50:53], v[188:191], v[196:199], v[50:53]
	v_mfma_f32_16x16x32_bf16 v[46:49], v[188:191], v[204:207], v[46:49]
	v_mfma_f32_16x16x32_bf16 v[42:45], v[188:191], v[208:211], v[42:45]
	s_waitcnt lgkmcnt(0)
	v_mfma_f32_16x16x32_bf16 v[38:41], v[246:249], v[192:195], v[38:41]
	v_mfma_f32_16x16x32_bf16 v[34:37], v[246:249], v[196:199], v[34:37]
	v_mfma_f32_16x16x32_bf16 v[30:33], v[246:249], v[204:207], v[30:33]
	v_mfma_f32_16x16x32_bf16 v[26:29], v[246:249], v[208:211], v[26:29]
	s_waitcnt lgkmcnt(0)
	s_setprio 0
	s_add_i32 s12, s12, 1
	v_lshl_add_u64 v[180:181], v[180:181], 0, s[26:27]
	s_cmp_lg_u32 s12, 8
	v_lshl_add_u64 v[178:179], v[178:179], 0, s[26:27]
	s_barrier
	s_cbranch_scc1 .LBB0_26
	v_lshrrev_b32_e32 v204, 5, v175
	v_and_b32_e32 v205, 31, v175
	v_mul_u32_u24_e32 v204, 0x210, v204
	v_lshl_add_u32 v204, v205, 4, v204
	s_waitcnt vmcnt(6)
	ds_write_b128 v204, v[212:215]
	ds_write_b128 v204, v[216:219] offset:8448
	ds_write_b128 v204, v[220:223] offset:16896
	ds_write_b128 v204, v[224:227] offset:25344
	ds_write_b128 v204, v[234:237] offset:33792
	ds_write_b128 v204, v[238:241] offset:42240
	ds_write_b128 v204, v[242:245] offset:50688
	ds_write_b64 v204, v[228:229] offset:59136
	ds_write_b64 v204, v[250:251] offset:59144
	s_waitcnt lgkmcnt(0)
	s_barrier
; __device__ __forceinline__ float bf2f(u16 h) { return __uint_as_float(((u32)h) << 16); }
; __device__ __forceinline__ float sigmoidf_(float x) { return 1.0f / (1.0f + __expf(-x)); }
; __device__ __forceinline__ void phase_merge(const Params& p, u16* smem, volatile LAS unsigned* vb_) {
;     ...
; #pragma unroll
;       for (int i = 0; i < 4; ++i)
; #pragma unroll
;         for (int j = 0; j < 4; ++j)
; #pragma unroll
;           for (int r = 0; r < 4; ++r) {
;             const float g = sigmoidf_(bf2f(smem[(wm * 64 + i * 16 + (lane >> 4) * 4 + r) * 264 + wn * 64 + j * 16 + (lane & 15)]));
;             tot[i][j][r] += g * acc[i][j][r];
;             if (r == 3) __builtin_amdgcn_sched_barrier(0);
;           }
	ds_read_u16 v212, v94
	ds_read_u16 v213, v94 offset:528
	ds_read_u16 v214, v94 offset:1056
	ds_read_u16 v215, v94 offset:1584
	ds_read_u16 v216, v94 offset:32
	ds_read_u16 v217, v94 offset:560
	ds_read_u16 v218, v94 offset:1088
	ds_read_u16 v219, v94 offset:1616
	s_waitcnt lgkmcnt(0)
	ds_read_u16 v204, v94 offset:64
	ds_read_u16 v205, v94 offset:592
	ds_read_u16 v206, v94 offset:1120
	ds_read_u16 v207, v94 offset:1648
	ds_read_u16 v208, v94 offset:96
	ds_read_u16 v209, v94 offset:624
	ds_read_u16 v210, v94 offset:1152
	ds_read_u16 v211, v94 offset:1680
	v_lshlrev_b32_e32 v212, 16, v212
	v_lshlrev_b32_e32 v213, 16, v213
	v_lshlrev_b32_e32 v214, 16, v214
	v_lshlrev_b32_e32 v215, 16, v215
	v_lshlrev_b32_e32 v216, 16, v216
	v_lshlrev_b32_e32 v217, 16, v217
	v_lshlrev_b32_e32 v218, 16, v218
	v_lshlrev_b32_e32 v219, 16, v219
	v_mul_f32_e32 v212, 0xbfb8aa3b, v212
	v_mul_f32_e32 v213, 0xbfb8aa3b, v213
	v_mul_f32_e32 v214, 0xbfb8aa3b, v214
	v_mul_f32_e32 v215, 0xbfb8aa3b, v215
	v_mul_f32_e32 v216, 0xbfb8aa3b, v216
	v_mul_f32_e32 v217, 0xbfb8aa3b, v217
	v_mul_f32_e32 v218, 0xbfb8aa3b, v218
	v_mul_f32_e32 v219, 0xbfb8aa3b, v219
	v_min_f32_e32 v212, 0x42fc0000, v212
	v_min_f32_e32 v213, 0x42fc0000, v213
	v_min_f32_e32 v214, 0x42fc0000, v214
	v_min_f32_e32 v215, 0x42fc0000, v215
	v_min_f32_e32 v216, 0x42fc0000, v216
	v_min_f32_e32 v217, 0x42fc0000, v217
	v_min_f32_e32 v218, 0x42fc0000, v218
	v_min_f32_e32 v219, 0x42fc0000, v219
	v_exp_f32_e32 v212, v212
	v_exp_f32_e32 v213, v213
	v_exp_f32_e32 v214, v214
	v_exp_f32_e32 v215, v215
	v_exp_f32_e32 v216, v216
	v_exp_f32_e32 v217, v217
	v_exp_f32_e32 v218, v218
	v_exp_f32_e32 v219, v219
	v_add_f32_e32 v212, 1.0, v212
	v_add_f32_e32 v213, 1.0, v213
	v_add_f32_e32 v214, 1.0, v214
	v_add_f32_e32 v215, 1.0, v215
	v_add_f32_e32 v216, 1.0, v216
	v_add_f32_e32 v217, 1.0, v217
	v_add_f32_e32 v218, 1.0, v218
	v_add_f32_e32 v219, 1.0, v219
	v_rcp_f32_e32 v220, v212
	v_rcp_f32_e32 v221, v213
	v_rcp_f32_e32 v222, v214
	v_rcp_f32_e32 v223, v215
	v_rcp_f32_e32 v224, v216
	v_rcp_f32_e32 v225, v217
	v_rcp_f32_e32 v226, v218
	v_rcp_f32_e32 v227, v219
	v_fma_f32 v212, -v212, v220, 1.0
	v_fma_f32 v213, -v213, v221, 1.0
	v_fma_f32 v214, -v214, v222, 1.0
	v_fma_f32 v215, -v215, v223, 1.0
	v_fma_f32 v216, -v216, v224, 1.0
	v_fma_f32 v217, -v217, v225, 1.0
	v_fma_f32 v218, -v218, v226, 1.0
	v_fma_f32 v219, -v219, v227, 1.0
	v_fmac_f32_e32 v220, v212, v220
	v_fmac_f32_e32 v221, v213, v221
	v_fmac_f32_e32 v222, v214, v222
	v_fmac_f32_e32 v223, v215, v223
	v_fmac_f32_e32 v224, v216, v224
	v_fmac_f32_e32 v225, v217, v225
	v_fmac_f32_e32 v226, v218, v226
	v_fmac_f32_e32 v227, v219, v227
	v_fmac_f32_e32 v170, v86, v220
	v_fmac_f32_e32 v171, v87, v221
	v_fmac_f32_e32 v168, v88, v222
	v_fmac_f32_e32 v169, v89, v223
	v_fmac_f32_e32 v166, v82, v224
	v_fmac_f32_e32 v167, v83, v225
	v_fmac_f32_e32 v164, v84, v226
	v_fmac_f32_e32 v165, v85, v227
	s_waitcnt lgkmcnt(0)
	ds_read_u16 v212, v94 offset:8448
	ds_read_u16 v213, v94 offset:8976
	ds_read_u16 v214, v94 offset:9504
	ds_read_u16 v215, v94 offset:10032
	ds_read_u16 v216, v94 offset:8480
	ds_read_u16 v217, v94 offset:9008
	ds_read_u16 v218, v94 offset:9536
	ds_read_u16 v219, v94 offset:10064
	v_lshlrev_b32_e32 v204, 16, v204
	v_lshlrev_b32_e32 v205, 16, v205
	v_lshlrev_b32_e32 v206, 16, v206
	v_lshlrev_b32_e32 v207, 16, v207
	v_lshlrev_b32_e32 v208, 16, v208
	v_lshlrev_b32_e32 v209, 16, v209
	v_lshlrev_b32_e32 v210, 16, v210
	v_lshlrev_b32_e32 v211, 16, v211
	v_mul_f32_e32 v204, 0xbfb8aa3b, v204
	v_mul_f32_e32 v205, 0xbfb8aa3b, v205
	v_mul_f32_e32 v206, 0xbfb8aa3b, v206
	v_mul_f32_e32 v207, 0xbfb8aa3b, v207
	v_mul_f32_e32 v208, 0xbfb8aa3b, v208
	v_mul_f32_e32 v209, 0xbfb8aa3b, v209
	v_mul_f32_e32 v210, 0xbfb8aa3b, v210
	v_mul_f32_e32 v211, 0xbfb8aa3b, v211
	v_min_f32_e32 v204, 0x42fc0000, v204
	v_min_f32_e32 v205, 0x42fc0000, v205
	v_min_f32_e32 v206, 0x42fc0000, v206
	v_min_f32_e32 v207, 0x42fc0000, v207
	v_min_f32_e32 v208, 0x42fc0000, v208
	v_min_f32_e32 v209, 0x42fc0000, v209
	v_min_f32_e32 v210, 0x42fc0000, v210
	v_min_f32_e32 v211, 0x42fc0000, v211
	v_exp_f32_e32 v204, v204
	v_exp_f32_e32 v205, v205
	v_exp_f32_e32 v206, v206
	v_exp_f32_e32 v207, v207
	v_exp_f32_e32 v208, v208
	v_exp_f32_e32 v209, v209
	v_exp_f32_e32 v210, v210
	v_exp_f32_e32 v211, v211
	v_add_f32_e32 v204, 1.0, v204
	v_add_f32_e32 v205, 1.0, v205
	v_add_f32_e32 v206, 1.0, v206
	v_add_f32_e32 v207, 1.0, v207
	v_add_f32_e32 v208, 1.0, v208
	v_add_f32_e32 v209, 1.0, v209
	v_add_f32_e32 v210, 1.0, v210
	v_add_f32_e32 v211, 1.0, v211
	v_rcp_f32_e32 v220, v204
	v_rcp_f32_e32 v221, v205
	v_rcp_f32_e32 v222, v206
	v_rcp_f32_e32 v223, v207
	v_rcp_f32_e32 v224, v208
	v_rcp_f32_e32 v225, v209
	v_rcp_f32_e32 v226, v210
	v_rcp_f32_e32 v227, v211
	v_fma_f32 v204, -v204, v220, 1.0
	v_fma_f32 v205, -v205, v221, 1.0
	v_fma_f32 v206, -v206, v222, 1.0
	v_fma_f32 v207, -v207, v223, 1.0
	v_fma_f32 v208, -v208, v224, 1.0
	v_fma_f32 v209, -v209, v225, 1.0
	v_fma_f32 v210, -v210, v226, 1.0
	v_fma_f32 v211, -v211, v227, 1.0
	v_fmac_f32_e32 v220, v204, v220
	v_fmac_f32_e32 v221, v205, v221
	v_fmac_f32_e32 v222, v206, v222
	v_fmac_f32_e32 v223, v207, v223
	v_fmac_f32_e32 v224, v208, v224
	v_fmac_f32_e32 v225, v209, v225
	v_fmac_f32_e32 v226, v210, v226
	v_fmac_f32_e32 v227, v211, v227
	v_fmac_f32_e32 v162, v78, v220
	v_fmac_f32_e32 v163, v79, v221
	v_fmac_f32_e32 v160, v80, v222
	v_fmac_f32_e32 v161, v81, v223
	v_fmac_f32_e32 v158, v74, v224
	v_fmac_f32_e32 v159, v75, v225
	v_fmac_f32_e32 v156, v76, v226
	v_fmac_f32_e32 v157, v77, v227
	s_waitcnt lgkmcnt(0)
; __device__ __forceinline__ float bf2f(u16 h) { return __uint_as_float(((u32)h) << 16); }
; __device__ __forceinline__ float sigmoidf_(float x) { return 1.0f / (1.0f + __expf(-x)); }
; __device__ __forceinline__ void phase_merge(const Params& p, u16* smem, volatile LAS unsigned* vb_) {
;     ...
; #pragma unroll
;       for (int i = 0; i < 4; ++i)
; #pragma unroll
;         for (int j = 0; j < 4; ++j)
; #pragma unroll
;           for (int r = 0; r < 4; ++r) {
;             const float g = sigmoidf_(bf2f(smem[(wm * 64 + i * 16 + (lane >> 4) * 4 + r) * 264 + wn * 64 + j * 16 + (lane & 15)]));
;             tot[i][j][r] += g * acc[i][j][r];
;             if (r == 3) __builtin_amdgcn_sched_barrier(0);
;           }
	ds_read_u16 v204, v94 offset:8512
	ds_read_u16 v205, v94 offset:9040
	ds_read_u16 v206, v94 offset:9568
	ds_read_u16 v207, v94 offset:10096
	ds_read_u16 v208, v94 offset:8544
	ds_read_u16 v209, v94 offset:9072
	ds_read_u16 v210, v94 offset:9600
	ds_read_u16 v211, v94 offset:10128
	v_lshlrev_b32_e32 v212, 16, v212
	v_lshlrev_b32_e32 v213, 16, v213
	v_lshlrev_b32_e32 v214, 16, v214
	v_lshlrev_b32_e32 v215, 16, v215
	v_lshlrev_b32_e32 v216, 16, v216
	v_lshlrev_b32_e32 v217, 16, v217
	v_lshlrev_b32_e32 v218, 16, v218
	v_lshlrev_b32_e32 v219, 16, v219
	v_mul_f32_e32 v212, 0xbfb8aa3b, v212
	v_mul_f32_e32 v213, 0xbfb8aa3b, v213
	v_mul_f32_e32 v214, 0xbfb8aa3b, v214
	v_mul_f32_e32 v215, 0xbfb8aa3b, v215
	v_mul_f32_e32 v216, 0xbfb8aa3b, v216
	v_mul_f32_e32 v217, 0xbfb8aa3b, v217
	v_mul_f32_e32 v218, 0xbfb8aa3b, v218
	v_mul_f32_e32 v219, 0xbfb8aa3b, v219
	v_min_f32_e32 v212, 0x42fc0000, v212
	v_min_f32_e32 v213, 0x42fc0000, v213
	v_min_f32_e32 v214, 0x42fc0000, v214
	v_min_f32_e32 v215, 0x42fc0000, v215
	v_min_f32_e32 v216, 0x42fc0000, v216
	v_min_f32_e32 v217, 0x42fc0000, v217
	v_min_f32_e32 v218, 0x42fc0000, v218
	v_min_f32_e32 v219, 0x42fc0000, v219
	v_exp_f32_e32 v212, v212
	v_exp_f32_e32 v213, v213
	v_exp_f32_e32 v214, v214
	v_exp_f32_e32 v215, v215
	v_exp_f32_e32 v216, v216
	v_exp_f32_e32 v217, v217
	v_exp_f32_e32 v218, v218
	v_exp_f32_e32 v219, v219
	v_add_f32_e32 v212, 1.0, v212
	v_add_f32_e32 v213, 1.0, v213
	v_add_f32_e32 v214, 1.0, v214
	v_add_f32_e32 v215, 1.0, v215
	v_add_f32_e32 v216, 1.0, v216
	v_add_f32_e32 v217, 1.0, v217
	v_add_f32_e32 v218, 1.0, v218
	v_add_f32_e32 v219, 1.0, v219
	v_rcp_f32_e32 v220, v212
	v_rcp_f32_e32 v221, v213
	v_rcp_f32_e32 v222, v214
	v_rcp_f32_e32 v223, v215
	v_rcp_f32_e32 v224, v216
	v_rcp_f32_e32 v225, v217
	v_rcp_f32_e32 v226, v218
	v_rcp_f32_e32 v227, v219
	v_fma_f32 v212, -v212, v220, 1.0
	v_fma_f32 v213, -v213, v221, 1.0
	v_fma_f32 v214, -v214, v222, 1.0
	v_fma_f32 v215, -v215, v223, 1.0
	v_fma_f32 v216, -v216, v224, 1.0
	v_fma_f32 v217, -v217, v225, 1.0
	v_fma_f32 v218, -v218, v226, 1.0
	v_fma_f32 v219, -v219, v227, 1.0
	v_fmac_f32_e32 v220, v212, v220
	v_fmac_f32_e32 v221, v213, v221
	v_fmac_f32_e32 v222, v214, v222
	v_fmac_f32_e32 v223, v215, v223
	v_fmac_f32_e32 v224, v216, v224
	v_fmac_f32_e32 v225, v217, v225
	v_fmac_f32_e32 v226, v218, v226
	v_fmac_f32_e32 v227, v219, v227
	v_fmac_f32_e32 v154, v70, v220
	v_fmac_f32_e32 v155, v71, v221
	v_fmac_f32_e32 v152, v72, v222
	v_fmac_f32_e32 v153, v73, v223
	v_fmac_f32_e32 v150, v66, v224
	v_fmac_f32_e32 v151, v67, v225
	v_fmac_f32_e32 v148, v68, v226
	v_fmac_f32_e32 v149, v69, v227
	s_waitcnt lgkmcnt(0)
	ds_read_u16 v212, v94 offset:16896
	ds_read_u16 v213, v94 offset:17424
	ds_read_u16 v214, v94 offset:17952
	ds_read_u16 v215, v94 offset:18480
	ds_read_u16 v216, v94 offset:16928
	ds_read_u16 v217, v94 offset:17456
	ds_read_u16 v218, v94 offset:17984
	ds_read_u16 v219, v94 offset:18512
	v_lshlrev_b32_e32 v204, 16, v204
	v_lshlrev_b32_e32 v205, 16, v205
	v_lshlrev_b32_e32 v206, 16, v206
	v_lshlrev_b32_e32 v207, 16, v207
	v_lshlrev_b32_e32 v208, 16, v208
	v_lshlrev_b32_e32 v209, 16, v209
	v_lshlrev_b32_e32 v210, 16, v210
	v_lshlrev_b32_e32 v211, 16, v211
	v_mul_f32_e32 v204, 0xbfb8aa3b, v204
	v_mul_f32_e32 v205, 0xbfb8aa3b, v205
	v_mul_f32_e32 v206, 0xbfb8aa3b, v206
	v_mul_f32_e32 v207, 0xbfb8aa3b, v207
	v_mul_f32_e32 v208, 0xbfb8aa3b, v208
	v_mul_f32_e32 v209, 0xbfb8aa3b, v209
	v_mul_f32_e32 v210, 0xbfb8aa3b, v210
	v_mul_f32_e32 v211, 0xbfb8aa3b, v211
	v_min_f32_e32 v204, 0x42fc0000, v204
	v_min_f32_e32 v205, 0x42fc0000, v205
	v_min_f32_e32 v206, 0x42fc0000, v206
	v_min_f32_e32 v207, 0x42fc0000, v207
	v_min_f32_e32 v208, 0x42fc0000, v208
	v_min_f32_e32 v209, 0x42fc0000, v209
	v_min_f32_e32 v210, 0x42fc0000, v210
	v_min_f32_e32 v211, 0x42fc0000, v211
	v_exp_f32_e32 v204, v204
	v_exp_f32_e32 v205, v205
	v_exp_f32_e32 v206, v206
	v_exp_f32_e32 v207, v207
	v_exp_f32_e32 v208, v208
	v_exp_f32_e32 v209, v209
	v_exp_f32_e32 v210, v210
	v_exp_f32_e32 v211, v211
	v_add_f32_e32 v204, 1.0, v204
	v_add_f32_e32 v205, 1.0, v205
	v_add_f32_e32 v206, 1.0, v206
	v_add_f32_e32 v207, 1.0, v207
	v_add_f32_e32 v208, 1.0, v208
	v_add_f32_e32 v209, 1.0, v209
	v_add_f32_e32 v210, 1.0, v210
	v_add_f32_e32 v211, 1.0, v211
	v_rcp_f32_e32 v220, v204
	v_rcp_f32_e32 v221, v205
	v_rcp_f32_e32 v222, v206
	v_rcp_f32_e32 v223, v207
	v_rcp_f32_e32 v224, v208
	v_rcp_f32_e32 v225, v209
	v_rcp_f32_e32 v226, v210
	v_rcp_f32_e32 v227, v211
	v_fma_f32 v204, -v204, v220, 1.0
	v_fma_f32 v205, -v205, v221, 1.0
	v_fma_f32 v206, -v206, v222, 1.0
	v_fma_f32 v207, -v207, v223, 1.0
	v_fma_f32 v208, -v208, v224, 1.0
	v_fma_f32 v209, -v209, v225, 1.0
	v_fma_f32 v210, -v210, v226, 1.0
	v_fma_f32 v211, -v211, v227, 1.0
	v_fmac_f32_e32 v220, v204, v220
	v_fmac_f32_e32 v221, v205, v221
	v_fmac_f32_e32 v222, v206, v222
	v_fmac_f32_e32 v223, v207, v223
	v_fmac_f32_e32 v224, v208, v224
	v_fmac_f32_e32 v225, v209, v225
	v_fmac_f32_e32 v226, v210, v226
	v_fmac_f32_e32 v227, v211, v227
	v_fmac_f32_e32 v146, v62, v220
	v_fmac_f32_e32 v147, v63, v221
	v_fmac_f32_e32 v144, v64, v222
	v_fmac_f32_e32 v145, v65, v223
	v_fmac_f32_e32 v138, v58, v224
	v_fmac_f32_e32 v139, v59, v225
	v_fmac_f32_e32 v136, v60, v226
	v_fmac_f32_e32 v137, v61, v227
	s_waitcnt lgkmcnt(0)
; __device__ __forceinline__ float bf2f(u16 h) { return __uint_as_float(((u32)h) << 16); }
; __device__ __forceinline__ float sigmoidf_(float x) { return 1.0f / (1.0f + __expf(-x)); }
; __device__ __forceinline__ void phase_merge(const Params& p, u16* smem, volatile LAS unsigned* vb_) {
;     ...
; #pragma unroll
;       for (int i = 0; i < 4; ++i)
; #pragma unroll
;         for (int j = 0; j < 4; ++j)
; #pragma unroll
;           for (int r = 0; r < 4; ++r) {
;             const float g = sigmoidf_(bf2f(smem[(wm * 64 + i * 16 + (lane >> 4) * 4 + r) * 264 + wn * 64 + j * 16 + (lane & 15)]));
;             tot[i][j][r] += g * acc[i][j][r];
;             if (r == 3) __builtin_amdgcn_sched_barrier(0);
;           }
	ds_read_u16 v204, v94 offset:16960
	ds_read_u16 v205, v94 offset:17488
	ds_read_u16 v206, v94 offset:18016
	ds_read_u16 v207, v94 offset:18544
	ds_read_u16 v208, v94 offset:16992
	ds_read_u16 v209, v94 offset:17520
	ds_read_u16 v210, v94 offset:18048
	ds_read_u16 v211, v94 offset:18576
	v_lshlrev_b32_e32 v212, 16, v212
	v_lshlrev_b32_e32 v213, 16, v213
	v_lshlrev_b32_e32 v214, 16, v214
	v_lshlrev_b32_e32 v215, 16, v215
	v_lshlrev_b32_e32 v216, 16, v216
	v_lshlrev_b32_e32 v217, 16, v217
	v_lshlrev_b32_e32 v218, 16, v218
	v_lshlrev_b32_e32 v219, 16, v219
	v_mul_f32_e32 v212, 0xbfb8aa3b, v212
	v_mul_f32_e32 v213, 0xbfb8aa3b, v213
	v_mul_f32_e32 v214, 0xbfb8aa3b, v214
	v_mul_f32_e32 v215, 0xbfb8aa3b, v215
	v_mul_f32_e32 v216, 0xbfb8aa3b, v216
	v_mul_f32_e32 v217, 0xbfb8aa3b, v217
	v_mul_f32_e32 v218, 0xbfb8aa3b, v218
	v_mul_f32_e32 v219, 0xbfb8aa3b, v219
	v_min_f32_e32 v212, 0x42fc0000, v212
	v_min_f32_e32 v213, 0x42fc0000, v213
	v_min_f32_e32 v214, 0x42fc0000, v214
	v_min_f32_e32 v215, 0x42fc0000, v215
	v_min_f32_e32 v216, 0x42fc0000, v216
	v_min_f32_e32 v217, 0x42fc0000, v217
	v_min_f32_e32 v218, 0x42fc0000, v218
	v_min_f32_e32 v219, 0x42fc0000, v219
	v_exp_f32_e32 v212, v212
	v_exp_f32_e32 v213, v213
	v_exp_f32_e32 v214, v214
	v_exp_f32_e32 v215, v215
	v_exp_f32_e32 v216, v216
	v_exp_f32_e32 v217, v217
	v_exp_f32_e32 v218, v218
	v_exp_f32_e32 v219, v219
	v_add_f32_e32 v212, 1.0, v212
	v_add_f32_e32 v213, 1.0, v213
	v_add_f32_e32 v214, 1.0, v214
	v_add_f32_e32 v215, 1.0, v215
	v_add_f32_e32 v216, 1.0, v216
	v_add_f32_e32 v217, 1.0, v217
	v_add_f32_e32 v218, 1.0, v218
	v_add_f32_e32 v219, 1.0, v219
	v_rcp_f32_e32 v220, v212
	v_rcp_f32_e32 v221, v213
	v_rcp_f32_e32 v222, v214
	v_rcp_f32_e32 v223, v215
	v_rcp_f32_e32 v224, v216
	v_rcp_f32_e32 v225, v217
	v_rcp_f32_e32 v226, v218
	v_rcp_f32_e32 v227, v219
	v_fma_f32 v212, -v212, v220, 1.0
	v_fma_f32 v213, -v213, v221, 1.0
	v_fma_f32 v214, -v214, v222, 1.0
	v_fma_f32 v215, -v215, v223, 1.0
	v_fma_f32 v216, -v216, v224, 1.0
	v_fma_f32 v217, -v217, v225, 1.0
	v_fma_f32 v218, -v218, v226, 1.0
	v_fma_f32 v219, -v219, v227, 1.0
	v_fmac_f32_e32 v220, v212, v220
	v_fmac_f32_e32 v221, v213, v221
	v_fmac_f32_e32 v222, v214, v222
	v_fmac_f32_e32 v223, v215, v223
	v_fmac_f32_e32 v224, v216, v224
	v_fmac_f32_e32 v225, v217, v225
	v_fmac_f32_e32 v226, v218, v226
	v_fmac_f32_e32 v227, v219, v227
	v_fmac_f32_e32 v134, v54, v220
	v_fmac_f32_e32 v135, v55, v221
	v_fmac_f32_e32 v130, v56, v222
	v_fmac_f32_e32 v131, v57, v223
	v_fmac_f32_e32 v126, v50, v224
	v_fmac_f32_e32 v127, v51, v225
	v_fmac_f32_e32 v124, v52, v226
	v_fmac_f32_e32 v125, v53, v227
	s_waitcnt lgkmcnt(0)
	ds_read_u16 v212, v94 offset:25344
	ds_read_u16 v213, v94 offset:25872
	ds_read_u16 v214, v94 offset:26400
	ds_read_u16 v215, v94 offset:26928
	ds_read_u16 v216, v94 offset:25376
	ds_read_u16 v217, v94 offset:25904
	ds_read_u16 v218, v94 offset:26432
	ds_read_u16 v219, v94 offset:26960
	v_lshlrev_b32_e32 v204, 16, v204
	v_lshlrev_b32_e32 v205, 16, v205
	v_lshlrev_b32_e32 v206, 16, v206
	v_lshlrev_b32_e32 v207, 16, v207
	v_lshlrev_b32_e32 v208, 16, v208
	v_lshlrev_b32_e32 v209, 16, v209
	v_lshlrev_b32_e32 v210, 16, v210
	v_lshlrev_b32_e32 v211, 16, v211
	v_mul_f32_e32 v204, 0xbfb8aa3b, v204
	v_mul_f32_e32 v205, 0xbfb8aa3b, v205
	v_mul_f32_e32 v206, 0xbfb8aa3b, v206
	v_mul_f32_e32 v207, 0xbfb8aa3b, v207
	v_mul_f32_e32 v208, 0xbfb8aa3b, v208
	v_mul_f32_e32 v209, 0xbfb8aa3b, v209
	v_mul_f32_e32 v210, 0xbfb8aa3b, v210
	v_mul_f32_e32 v211, 0xbfb8aa3b, v211
	v_min_f32_e32 v204, 0x42fc0000, v204
	v_min_f32_e32 v205, 0x42fc0000, v205
	v_min_f32_e32 v206, 0x42fc0000, v206
	v_min_f32_e32 v207, 0x42fc0000, v207
	v_min_f32_e32 v208, 0x42fc0000, v208
	v_min_f32_e32 v209, 0x42fc0000, v209
	v_min_f32_e32 v210, 0x42fc0000, v210
	v_min_f32_e32 v211, 0x42fc0000, v211
	v_exp_f32_e32 v204, v204
	v_exp_f32_e32 v205, v205
	v_exp_f32_e32 v206, v206
	v_exp_f32_e32 v207, v207
	v_exp_f32_e32 v208, v208
	v_exp_f32_e32 v209, v209
	v_exp_f32_e32 v210, v210
	v_exp_f32_e32 v211, v211
	v_add_f32_e32 v204, 1.0, v204
	v_add_f32_e32 v205, 1.0, v205
	v_add_f32_e32 v206, 1.0, v206
	v_add_f32_e32 v207, 1.0, v207
	v_add_f32_e32 v208, 1.0, v208
	v_add_f32_e32 v209, 1.0, v209
	v_add_f32_e32 v210, 1.0, v210
	v_add_f32_e32 v211, 1.0, v211
	v_rcp_f32_e32 v220, v204
	v_rcp_f32_e32 v221, v205
	v_rcp_f32_e32 v222, v206
	v_rcp_f32_e32 v223, v207
	v_rcp_f32_e32 v224, v208
	v_rcp_f32_e32 v225, v209
	v_rcp_f32_e32 v226, v210
	v_rcp_f32_e32 v227, v211
	v_fma_f32 v204, -v204, v220, 1.0
	v_fma_f32 v205, -v205, v221, 1.0
	v_fma_f32 v206, -v206, v222, 1.0
	v_fma_f32 v207, -v207, v223, 1.0
	v_fma_f32 v208, -v208, v224, 1.0
	v_fma_f32 v209, -v209, v225, 1.0
	v_fma_f32 v210, -v210, v226, 1.0
	v_fma_f32 v211, -v211, v227, 1.0
	v_fmac_f32_e32 v220, v204, v220
	v_fmac_f32_e32 v221, v205, v221
	v_fmac_f32_e32 v222, v206, v222
	v_fmac_f32_e32 v223, v207, v223
	v_fmac_f32_e32 v224, v208, v224
	v_fmac_f32_e32 v225, v209, v225
	v_fmac_f32_e32 v226, v210, v226
	v_fmac_f32_e32 v227, v211, v227
	v_fmac_f32_e32 v122, v46, v220
	v_fmac_f32_e32 v123, v47, v221
	v_fmac_f32_e32 v120, v48, v222
	v_fmac_f32_e32 v121, v49, v223
	v_fmac_f32_e32 v118, v42, v224
	v_fmac_f32_e32 v119, v43, v225
	v_fmac_f32_e32 v116, v44, v226
	v_fmac_f32_e32 v117, v45, v227
	s_waitcnt lgkmcnt(0)
; #define RTID opaque_tid()
; __device__ __forceinline__ float bf2f(u16 h) { return __uint_as_float(((u32)h) << 16); }
; __device__ __forceinline__ float sigmoidf_(float x) { return 1.0f / (1.0f + __expf(-x)); }
; #define ZERO_ACC(acc)                                  \
;   _Pragma("unroll") for (int i_ = 0; i_ < 4; ++i_)     \
;   _Pragma("unroll") for (int j_ = 0; j_ < 4; ++j_) { acc[i_][j_] = (f32x4){0.f, 0.f, 0.f, 0.f}; }
; __device__ __forceinline__ void phase_merge(const Params& p, u16* smem, volatile LAS unsigned* vb_) {
;     ...
;     for (int n = 0; n < 3; ++n) {
;       f32x4 acc[4][4];
;       ZERO_ACC(acc);
;       gemm8<4, 4>(acc, G8REGS_ARGS, pre, Y, 1536, W, 1536, n * 512, n * 512 + 512, mt * 128, nt * 256,
;                   (n < 2) ? mt * 128 : nmt * 128, (n < 2) ? nt * 256 : nnt * 256, (n < 2) ? (n + 1) * 512 : 0, smem, tid);
;       pre = true;
;       const int tid2 = RTID;
; #pragma unroll
;       for (int k = 0; k < 8; ++k) {
;         const int c = tid2 + 512 * k;
;         const int row = c >> 5, ch = c & 31;
;         *(uint4*)(smem + row * 264 + ch * 8) = *(const uint4*)(MG + (size_t)(mt * 128 + row) * 3072 + n * 1024 + nt * 256 + ch * 8);
;       }
;       __syncthreads();
; #pragma unroll
;       for (int i = 0; i < 4; ++i)
; #pragma unroll
;         for (int j = 0; j < 4; ++j)
; #pragma unroll
;           for (int r = 0; r < 4; ++r) {
;             const float g = sigmoidf_(bf2f(smem[(wm * 64 + i * 16 + (lane >> 4) * 4 + r) * 264 + wn * 64 + j * 16 + (lane & 15)]));
;             tot[i][j][r] += g * acc[i][j][r];
;             if (r == 3) __builtin_amdgcn_sched_barrier(0);
;           }
;       __syncthreads();
;     }
	ds_read_u16 v204, v94 offset:25408
	ds_read_u16 v205, v94 offset:25936
	ds_read_u16 v206, v94 offset:26464
	ds_read_u16 v207, v94 offset:26992
	ds_read_u16 v208, v94 offset:25440
	ds_read_u16 v209, v94 offset:25968
	ds_read_u16 v210, v94 offset:26496
	ds_read_u16 v211, v94 offset:27024
	v_lshlrev_b32_e32 v212, 16, v212
	v_lshlrev_b32_e32 v213, 16, v213
	v_lshlrev_b32_e32 v214, 16, v214
	v_lshlrev_b32_e32 v215, 16, v215
	v_lshlrev_b32_e32 v216, 16, v216
	v_lshlrev_b32_e32 v217, 16, v217
	v_lshlrev_b32_e32 v218, 16, v218
	v_lshlrev_b32_e32 v219, 16, v219
	v_mul_f32_e32 v212, 0xbfb8aa3b, v212
	v_mul_f32_e32 v213, 0xbfb8aa3b, v213
	v_mul_f32_e32 v214, 0xbfb8aa3b, v214
	v_mul_f32_e32 v215, 0xbfb8aa3b, v215
	v_mul_f32_e32 v216, 0xbfb8aa3b, v216
	v_mul_f32_e32 v217, 0xbfb8aa3b, v217
	v_mul_f32_e32 v218, 0xbfb8aa3b, v218
	v_mul_f32_e32 v219, 0xbfb8aa3b, v219
	v_min_f32_e32 v212, 0x42fc0000, v212
	v_min_f32_e32 v213, 0x42fc0000, v213
	v_min_f32_e32 v214, 0x42fc0000, v214
	v_min_f32_e32 v215, 0x42fc0000, v215
	v_min_f32_e32 v216, 0x42fc0000, v216
	v_min_f32_e32 v217, 0x42fc0000, v217
	v_min_f32_e32 v218, 0x42fc0000, v218
	v_min_f32_e32 v219, 0x42fc0000, v219
	v_exp_f32_e32 v212, v212
	v_exp_f32_e32 v213, v213
	v_exp_f32_e32 v214, v214
	v_exp_f32_e32 v215, v215
	v_exp_f32_e32 v216, v216
	v_exp_f32_e32 v217, v217
	v_exp_f32_e32 v218, v218
	v_exp_f32_e32 v219, v219
	v_add_f32_e32 v212, 1.0, v212
	v_add_f32_e32 v213, 1.0, v213
	v_add_f32_e32 v214, 1.0, v214
	v_add_f32_e32 v215, 1.0, v215
	v_add_f32_e32 v216, 1.0, v216
	v_add_f32_e32 v217, 1.0, v217
	v_add_f32_e32 v218, 1.0, v218
	v_add_f32_e32 v219, 1.0, v219
	v_rcp_f32_e32 v220, v212
	v_rcp_f32_e32 v221, v213
	v_rcp_f32_e32 v222, v214
	v_rcp_f32_e32 v223, v215
	v_rcp_f32_e32 v224, v216
	v_rcp_f32_e32 v225, v217
	v_rcp_f32_e32 v226, v218
	v_rcp_f32_e32 v227, v219
	v_fma_f32 v212, -v212, v220, 1.0
	v_fma_f32 v213, -v213, v221, 1.0
	v_fma_f32 v214, -v214, v222, 1.0
	v_fma_f32 v215, -v215, v223, 1.0
	v_fma_f32 v216, -v216, v224, 1.0
	v_fma_f32 v217, -v217, v225, 1.0
	v_fma_f32 v218, -v218, v226, 1.0
	v_fma_f32 v219, -v219, v227, 1.0
	v_fmac_f32_e32 v220, v212, v220
	v_fmac_f32_e32 v221, v213, v221
	v_fmac_f32_e32 v222, v214, v222
	v_fmac_f32_e32 v223, v215, v223
	v_fmac_f32_e32 v224, v216, v224
	v_fmac_f32_e32 v225, v217, v225
	v_fmac_f32_e32 v226, v218, v226
	v_fmac_f32_e32 v227, v219, v227
	v_fmac_f32_e32 v114, v38, v220
	v_fmac_f32_e32 v115, v39, v221
	v_fmac_f32_e32 v112, v40, v222
	v_fmac_f32_e32 v113, v41, v223
	v_fmac_f32_e32 v110, v34, v224
	v_fmac_f32_e32 v111, v35, v225
	v_fmac_f32_e32 v108, v36, v226
	v_fmac_f32_e32 v109, v37, v227
	s_waitcnt lgkmcnt(0)
	v_lshlrev_b32_e32 v204, 16, v204
	v_lshlrev_b32_e32 v205, 16, v205
	v_lshlrev_b32_e32 v206, 16, v206
	v_lshlrev_b32_e32 v207, 16, v207
	v_lshlrev_b32_e32 v208, 16, v208
	v_lshlrev_b32_e32 v209, 16, v209
	v_lshlrev_b32_e32 v210, 16, v210
	v_lshlrev_b32_e32 v211, 16, v211
	v_mul_f32_e32 v204, 0xbfb8aa3b, v204
	v_mul_f32_e32 v205, 0xbfb8aa3b, v205
	v_mul_f32_e32 v206, 0xbfb8aa3b, v206
	v_mul_f32_e32 v207, 0xbfb8aa3b, v207
	v_mul_f32_e32 v208, 0xbfb8aa3b, v208
	v_mul_f32_e32 v209, 0xbfb8aa3b, v209
	v_mul_f32_e32 v210, 0xbfb8aa3b, v210
	v_mul_f32_e32 v211, 0xbfb8aa3b, v211
	v_min_f32_e32 v204, 0x42fc0000, v204
	v_min_f32_e32 v205, 0x42fc0000, v205
	v_min_f32_e32 v206, 0x42fc0000, v206
	v_min_f32_e32 v207, 0x42fc0000, v207
	v_min_f32_e32 v208, 0x42fc0000, v208
	v_min_f32_e32 v209, 0x42fc0000, v209
	v_min_f32_e32 v210, 0x42fc0000, v210
	v_min_f32_e32 v211, 0x42fc0000, v211
	v_exp_f32_e32 v204, v204
	v_exp_f32_e32 v205, v205
	v_exp_f32_e32 v206, v206
	v_exp_f32_e32 v207, v207
	v_exp_f32_e32 v208, v208
	v_exp_f32_e32 v209, v209
	v_exp_f32_e32 v210, v210
	v_exp_f32_e32 v211, v211
	v_add_f32_e32 v204, 1.0, v204
	v_add_f32_e32 v205, 1.0, v205
	v_add_f32_e32 v206, 1.0, v206
	v_add_f32_e32 v207, 1.0, v207
	v_add_f32_e32 v208, 1.0, v208
	v_add_f32_e32 v209, 1.0, v209
	v_add_f32_e32 v210, 1.0, v210
	v_add_f32_e32 v211, 1.0, v211
	v_rcp_f32_e32 v220, v204
	v_rcp_f32_e32 v221, v205
	v_rcp_f32_e32 v222, v206
	v_rcp_f32_e32 v223, v207
	v_rcp_f32_e32 v224, v208
	v_rcp_f32_e32 v225, v209
	v_rcp_f32_e32 v226, v210
	v_rcp_f32_e32 v227, v211
	v_fma_f32 v204, -v204, v220, 1.0
	v_fma_f32 v205, -v205, v221, 1.0
	v_fma_f32 v206, -v206, v222, 1.0
	v_fma_f32 v207, -v207, v223, 1.0
	v_fma_f32 v208, -v208, v224, 1.0
	v_fma_f32 v209, -v209, v225, 1.0
	v_fma_f32 v210, -v210, v226, 1.0
	v_fma_f32 v211, -v211, v227, 1.0
	v_fmac_f32_e32 v220, v204, v220
	v_fmac_f32_e32 v221, v205, v221
	v_fmac_f32_e32 v222, v206, v222
	v_fmac_f32_e32 v223, v207, v223
	v_fmac_f32_e32 v224, v208, v224
	v_fmac_f32_e32 v225, v209, v225
	v_fmac_f32_e32 v226, v210, v226
	v_fmac_f32_e32 v227, v211, v227
	v_fmac_f32_e32 v106, v30, v220
	v_fmac_f32_e32 v107, v31, v221
	v_fmac_f32_e32 v104, v32, v222
	v_fmac_f32_e32 v105, v33, v223
	v_fmac_f32_e32 v100, v26, v224
	v_fmac_f32_e32 v101, v27, v225
	v_fmac_f32_e32 v102, v28, v226
	v_fmac_f32_e32 v103, v29, v227
	s_add_i32 s39, s39, 1
	v_lshl_add_u64 v[128:129], v[128:129], 0, s[18:19]
	v_lshl_add_u64 v[132:133], v[132:133], 0, s[18:19]
	s_cmp_eq_u32 s39, 3
	s_mov_b64 s[12:13], -1
	s_barrier
	s_cbranch_scc0 .LBB0_23
; __device__ __forceinline__ void phase_merge(const Params& p, u16* smem, volatile LAS unsigned* vb_) {
;     ...
; #pragma unroll
;     for (int i = 0; i < 4; ++i)
; #pragma unroll
;       for (int j = 0; j < 4; ++j)
; #pragma unroll
;         for (int r = 0; r < 4; ++r)
;           smem[(wm * 64 + i * 16 + (lane >> 4) * 4 + r) * 264 + wn * 64 + j * 16 + (lane & 15)] = f2bf(tot[i][j][r]);
;     __syncthreads();
	v_cvt_pk_bf16_f32 v0, v170, s0
	ds_write_b16 v94, v0
	v_cvt_pk_bf16_f32 v0, v171, s0
	ds_write_b16 v94, v0 offset:528
	v_cvt_pk_bf16_f32 v0, v168, s0
	ds_write_b16 v94, v0 offset:1056
	v_cvt_pk_bf16_f32 v0, v169, s0
	ds_write_b16 v94, v0 offset:1584
	v_cvt_pk_bf16_f32 v0, v166, s0
	ds_write_b16 v94, v0 offset:32
	v_cvt_pk_bf16_f32 v0, v167, s0
	ds_write_b16 v94, v0 offset:560
	v_cvt_pk_bf16_f32 v0, v164, s0
	ds_write_b16 v94, v0 offset:1088
	v_cvt_pk_bf16_f32 v0, v165, s0
	ds_write_b16 v94, v0 offset:1616
	v_cvt_pk_bf16_f32 v0, v162, s0
	ds_write_b16 v94, v0 offset:64
	v_cvt_pk_bf16_f32 v0, v163, s0
	ds_write_b16 v94, v0 offset:592
	v_cvt_pk_bf16_f32 v0, v160, s0
	ds_write_b16 v94, v0 offset:1120
	v_cvt_pk_bf16_f32 v0, v161, s0
	ds_write_b16 v94, v0 offset:1648
	v_cvt_pk_bf16_f32 v0, v158, s0
	ds_write_b16 v94, v0 offset:96
	v_cvt_pk_bf16_f32 v0, v159, s0
	ds_write_b16 v94, v0 offset:624
	v_cvt_pk_bf16_f32 v0, v156, s0
	ds_write_b16 v94, v0 offset:1152
	v_cvt_pk_bf16_f32 v0, v157, s0
	ds_write_b16 v94, v0 offset:1680
	v_cvt_pk_bf16_f32 v0, v154, s0
	ds_write_b16 v94, v0 offset:8448
	v_cvt_pk_bf16_f32 v0, v155, s0
	ds_write_b16 v94, v0 offset:8976
	v_cvt_pk_bf16_f32 v0, v152, s0
	ds_write_b16 v94, v0 offset:9504
	v_cvt_pk_bf16_f32 v0, v153, s0
	ds_write_b16 v94, v0 offset:10032
	v_cvt_pk_bf16_f32 v0, v150, s0
	ds_write_b16 v94, v0 offset:8480
	v_cvt_pk_bf16_f32 v0, v151, s0
	ds_write_b16 v94, v0 offset:9008
	v_cvt_pk_bf16_f32 v0, v148, s0
	ds_write_b16 v94, v0 offset:9536
	v_cvt_pk_bf16_f32 v0, v149, s0
	ds_write_b16 v94, v0 offset:10064
	v_cvt_pk_bf16_f32 v0, v146, s0
	ds_write_b16 v94, v0 offset:8512
	v_cvt_pk_bf16_f32 v0, v147, s0
	ds_write_b16 v94, v0 offset:9040
	v_cvt_pk_bf16_f32 v0, v144, s0
	ds_write_b16 v94, v0 offset:9568
	v_cvt_pk_bf16_f32 v0, v145, s0
	ds_write_b16 v94, v0 offset:10096
	v_cvt_pk_bf16_f32 v0, v138, s0
	ds_write_b16 v94, v0 offset:8544
	v_cvt_pk_bf16_f32 v0, v139, s0
	ds_write_b16 v94, v0 offset:9072
	v_cvt_pk_bf16_f32 v0, v136, s0
	ds_write_b16 v94, v0 offset:9600
	v_cvt_pk_bf16_f32 v0, v137, s0
	ds_write_b16 v94, v0 offset:10128
	v_cvt_pk_bf16_f32 v0, v134, s0
	ds_write_b16 v94, v0 offset:16896
	v_cvt_pk_bf16_f32 v0, v135, s0
	ds_write_b16 v94, v0 offset:17424
	v_cvt_pk_bf16_f32 v0, v130, s0
	ds_write_b16 v94, v0 offset:17952
	v_cvt_pk_bf16_f32 v0, v131, s0
	ds_write_b16 v94, v0 offset:18480
	v_cvt_pk_bf16_f32 v0, v126, s0
	ds_write_b16 v94, v0 offset:16928
	v_cvt_pk_bf16_f32 v0, v127, s0
	ds_write_b16 v94, v0 offset:17456
	v_cvt_pk_bf16_f32 v0, v124, s0
	ds_write_b16 v94, v0 offset:17984
	v_cvt_pk_bf16_f32 v0, v125, s0
	ds_write_b16 v94, v0 offset:18512
	v_cvt_pk_bf16_f32 v0, v122, s0
	ds_write_b16 v94, v0 offset:16960
	v_cvt_pk_bf16_f32 v0, v123, s0
	ds_write_b16 v94, v0 offset:17488
	v_cvt_pk_bf16_f32 v0, v120, s0
	ds_write_b16 v94, v0 offset:18016
	v_cvt_pk_bf16_f32 v0, v121, s0
	ds_write_b16 v94, v0 offset:18544
	v_cvt_pk_bf16_f32 v0, v118, s0
	ds_write_b16 v94, v0 offset:16992
	v_cvt_pk_bf16_f32 v0, v119, s0
	ds_write_b16 v94, v0 offset:17520
	v_cvt_pk_bf16_f32 v0, v116, s0
	ds_write_b16 v94, v0 offset:18048
	v_cvt_pk_bf16_f32 v0, v117, s0
	ds_write_b16 v94, v0 offset:18576
	v_cvt_pk_bf16_f32 v0, v114, s0
	ds_write_b16 v94, v0 offset:25344
	v_cvt_pk_bf16_f32 v0, v115, s0
	ds_write_b16 v94, v0 offset:25872
	v_cvt_pk_bf16_f32 v0, v112, s0
	ds_write_b16 v94, v0 offset:26400
	v_cvt_pk_bf16_f32 v0, v113, s0
	ds_write_b16 v94, v0 offset:26928
	v_cvt_pk_bf16_f32 v0, v110, s0
	ds_write_b16 v94, v0 offset:25376
	v_cvt_pk_bf16_f32 v0, v111, s0
	ds_write_b16 v94, v0 offset:25904
	v_cvt_pk_bf16_f32 v0, v108, s0
	ds_write_b16 v94, v0 offset:26432
	v_cvt_pk_bf16_f32 v0, v109, s0
	ds_write_b16 v94, v0 offset:26960
	v_cvt_pk_bf16_f32 v0, v106, s0
	ds_write_b16 v94, v0 offset:25408
	v_cvt_pk_bf16_f32 v0, v107, s0
	ds_write_b16 v94, v0 offset:25936
	v_cvt_pk_bf16_f32 v0, v104, s0
	ds_write_b16 v94, v0 offset:26464
	v_cvt_pk_bf16_f32 v0, v105, s0
	ds_write_b16 v94, v0 offset:26992
	v_cvt_pk_bf16_f32 v0, v100, s0
	ds_write_b16 v94, v0 offset:25440
	v_cvt_pk_bf16_f32 v0, v101, s0
	ds_write_b16 v94, v0 offset:25968
	v_cvt_pk_bf16_f32 v0, v102, s0
	ds_write_b16 v94, v0 offset:26496
	v_cvt_pk_bf16_f32 v0, v103, s0
	v_mov_b32_e32 v38, v175
	v_readlane_b32 s12, v252, 38
	ds_write_b16 v94, v0 offset:27024
	s_waitcnt lgkmcnt(0)
	s_barrier
; #define RTID opaque_tid()
; __device__ __forceinline__ void phase_merge(const Params& p, u16* smem, volatile LAS unsigned* vb_) {
;     ...
;     const int tid3 = RTID;
; #pragma unroll
;     for (int k = 0; k < 8; ++k) {
;       const int c = tid3 + 512 * k;
;       const int row = c >> 5, ch = c & 31;
;       *(uint4*)(outp + (size_t)(mt * 128 + row) * 1024 + nt * 256 + ch * 8) = *(const uint4*)(smem + row * 264 + ch * 8);
;     }
;     __syncthreads();
;   }
	v_readlane_b32 s13, v252, 39
	v_lshlrev_b32_e32 v0, 4, v38
	s_add_u32 s12, s12, s42
	v_and_b32_e32 v0, 0x1f0, v0
	s_addc_u32 s13, s13, s43
	v_ashrrev_i32_e32 v28, 5, v38
	v_lshl_add_u64 v[34:35], s[12:13], 0, v[0:1]
	v_mad_u64_u32 v[26:27], s[12:13], v28, s2, v[0:1]
	v_add_u32_e32 v28, s22, v28
	v_ashrrev_i32_e32 v29, 31, v28
	v_lshlrev_b64 v[28:29], 11, v[28:29]
	v_lshl_add_u64 v[36:37], v[34:35], 0, v[28:29]
	ds_read_b128 v[26:29], v26
	v_add_u32_e32 v30, 0x200, v38
	v_ashrrev_i32_e32 v39, 5, v30
	v_mad_u64_u32 v[30:31], s[12:13], v39, s2, v[0:1]
	ds_read_b128 v[30:33], v30
	s_waitcnt lgkmcnt(1)
	global_store_dwordx4 v[36:37], v[26:29], off
	s_add_i32 s10, s10, s70
	s_and_b64 vcc, exec, s[0:1]
	v_add_u32_e32 v26, s22, v39
	v_ashrrev_i32_e32 v27, 31, v26
	v_lshlrev_b64 v[26:27], 11, v[26:27]
	v_lshl_add_u64 v[26:27], v[34:35], 0, v[26:27]
	s_waitcnt lgkmcnt(0)
	global_store_dwordx4 v[26:27], v[30:33], off
	v_add_u32_e32 v26, 0x400, v38
	v_ashrrev_i32_e32 v28, 5, v26
	v_mad_u64_u32 v[26:27], s[12:13], v28, s2, v[0:1]
	v_add_u32_e32 v28, s22, v28
	v_ashrrev_i32_e32 v29, 31, v28
	v_lshlrev_b64 v[28:29], 11, v[28:29]
	v_lshl_add_u64 v[36:37], v[34:35], 0, v[28:29]
	ds_read_b128 v[26:29], v26
	v_add_u32_e32 v30, 0x600, v38
	v_ashrrev_i32_e32 v39, 5, v30
	v_mad_u64_u32 v[30:31], s[12:13], v39, s2, v[0:1]
	ds_read_b128 v[30:33], v30
	s_waitcnt lgkmcnt(1)
	global_store_dwordx4 v[36:37], v[26:29], off
	s_nop 1
	v_add_u32_e32 v26, s22, v39
	v_ashrrev_i32_e32 v27, 31, v26
	v_lshlrev_b64 v[26:27], 11, v[26:27]
	v_lshl_add_u64 v[26:27], v[34:35], 0, v[26:27]
	s_waitcnt lgkmcnt(0)
	global_store_dwordx4 v[26:27], v[30:33], off
	v_add_u32_e32 v26, 0x800, v38
	v_ashrrev_i32_e32 v28, 5, v26
	v_mad_u64_u32 v[26:27], s[12:13], v28, s2, v[0:1]
	v_add_u32_e32 v28, s22, v28
	v_ashrrev_i32_e32 v29, 31, v28
	v_lshlrev_b64 v[28:29], 11, v[28:29]
	v_lshl_add_u64 v[36:37], v[34:35], 0, v[28:29]
	ds_read_b128 v[26:29], v26
	v_add_u32_e32 v30, 0xa00, v38
	v_ashrrev_i32_e32 v39, 5, v30
	v_mad_u64_u32 v[30:31], s[12:13], v39, s2, v[0:1]
	ds_read_b128 v[30:33], v30
	s_waitcnt lgkmcnt(1)
	global_store_dwordx4 v[36:37], v[26:29], off
	s_nop 1
	v_add_u32_e32 v26, s22, v39
	v_ashrrev_i32_e32 v27, 31, v26
	v_lshlrev_b64 v[26:27], 11, v[26:27]
	v_lshl_add_u64 v[26:27], v[34:35], 0, v[26:27]
	s_waitcnt lgkmcnt(0)
	global_store_dwordx4 v[26:27], v[30:33], off
	v_add_u32_e32 v26, 0xc00, v38
	v_ashrrev_i32_e32 v28, 5, v26
	v_mad_u64_u32 v[26:27], s[12:13], v28, s2, v[0:1]
	v_add_u32_e32 v28, s22, v28
	v_ashrrev_i32_e32 v29, 31, v28
	v_lshlrev_b64 v[28:29], 11, v[28:29]
	v_lshl_add_u64 v[36:37], v[34:35], 0, v[28:29]
	ds_read_b128 v[26:29], v26
	v_add_u32_e32 v30, 0xe00, v38
	v_ashrrev_i32_e32 v38, 5, v30
	v_mad_u64_u32 v[30:31], s[12:13], v38, s2, v[0:1]
	ds_read_b128 v[30:33], v30
	s_waitcnt lgkmcnt(1)
	global_store_dwordx4 v[36:37], v[26:29], off
	v_readlane_b32 s12, v254, 30
	s_add_i32 s21, s21, s12
	v_add_u32_e32 v26, s22, v38
	v_ashrrev_i32_e32 v27, 31, v26
	v_lshlrev_b64 v[26:27], 11, v[26:27]
	v_lshl_add_u64 v[26:27], v[34:35], 0, v[26:27]
	s_mov_b64 s[12:13], -1
	s_waitcnt lgkmcnt(0)
	global_store_dwordx4 v[26:27], v[30:33], off
	s_barrier
	s_cbranch_vccz .LBB0_22
